# attention: first sub-tile max tree finished and its cross-half exchange issued before the second tree (both steps)
# baseline (speedup 1.0000x reference)
; #define LAS __attribute__((address_space(3)))
; #define MFMA32(a, b, c) __builtin_amdgcn_mfma_f32_32x32x16_bf16((a), (b), (c), 0, 0, 0)
; #define AT_LMAX(P, MX) do { MX = fmaxf(fmaxf(P[0], P[1]), fmaxf(P[2], P[3])); \
;         _Pragma("unroll") for (int i_ = 4; i_ < 16; i_ += 4) MX = fmaxf(fmaxf(MX, P[i_]), fmaxf(fmaxf(P[i_ + 1], P[i_ + 2]), P[i_ + 3])); } while (0)
; __device__ __forceinline__ void attn_unit(LAS unsigned char* lds, const GAS bf16_t* __restrict__ QR, const GAS float* __restrict__ ssq, const GAS float* __restrict__ RT, const GAS bf16_t* __restrict__ K, const GAS bf16_t* __restrict__ Vt, GAS bf16_t* __restrict__ A2, int b, int h, int qb, int tid, i ...
;     ...
;             const LAS unsigned char* kb = sb + (32 * hh + r32s) * AT_KROW + hi * 16;
;             f32x16 pA, pB;
; #pragma unroll
;             for (int i = 0; i < 16; ++i) { pA[i] = 0.f; pB[i] = 0.f; }
; #pragma unroll
;             for (int d0 = 0; d0 < 6; ++d0) { const bf16x8 a0 = *(const LAS bf16x8*)(kb + d0 * 32); pA = MFMA32(a0, qa[d0], pA); pB = MFMA32(a0, qc[d0], pB); }
;             u32x4 pwA0, pwA1, pwB0, pwB1;
;             float mxA, mxB; AT_LMAX(pA, mxA); AT_LMAX(pB, mxB);
;             { const float oa = __shfl_xor(mxA, 32), ob = __shfl_xor(mxB, 32); mxA = fmaxf(mxA, oa); mxB = fmaxf(mxB, ob); }
;             AT_SOFTMAX(pA, mxA, mA, lA, oA0, oA1, pwA0, pwA1);
;             AT_SOFTMAX(pB, mxB, mB, lB, oB0, oB1, pwB0, pwB1);
.LBB0_139:
	s_mul_i32 s22, s1, 0x5800
	s_add_i32 s24, s22, 0
	v_add_u32_e32 v212, s24, v1
	ds_read_b128 v[66:69], v212
	ds_read_b128 v[214:217], v212 offset:32
	ds_read_b128 v[218:221], v212 offset:64
	ds_read_b128 v[222:225], v212 offset:96
	ds_read_b128 v[226:229], v212 offset:128
	ds_read_b128 v[230:233], v212 offset:160
	s_waitcnt lgkmcnt(5)
	v_mfma_f32_32x32x16_bf16 v[82:97], v[66:69], v[98:101], v[188:203]
	s_waitcnt lgkmcnt(4)
	v_mfma_f32_32x32x16_bf16 v[82:97], v[214:217], v[102:105], v[82:97]
	s_waitcnt lgkmcnt(3)
	v_mfma_f32_32x32x16_bf16 v[82:97], v[218:221], v[106:109], v[82:97]
	s_waitcnt lgkmcnt(2)
	v_mfma_f32_32x32x16_bf16 v[82:97], v[222:225], v[110:113], v[82:97]
	s_waitcnt lgkmcnt(1)
	v_mfma_f32_32x32x16_bf16 v[82:97], v[226:229], v[134:137], v[82:97]
	s_waitcnt lgkmcnt(0)
	v_mfma_f32_32x32x16_bf16 v[82:97], v[230:233], v[114:117], v[82:97]
	v_mfma_f32_32x32x16_bf16 v[66:81], v[66:69], v[118:121], v[234:249]
	v_mfma_f32_32x32x16_bf16 v[66:81], v[214:217], v[122:125], v[66:81]
	v_mfma_f32_32x32x16_bf16 v[66:81], v[218:221], v[126:129], v[66:81]
	v_mfma_f32_32x32x16_bf16 v[66:81], v[222:225], v[130:133], v[66:81]
	v_mfma_f32_32x32x16_bf16 v[66:81], v[226:229], v[138:141], v[66:81]
	v_mfma_f32_32x32x16_bf16 v[66:81], v[230:233], v[142:145], v[66:81]
	s_nop 5
	v_max_f32_e32 v210, v84, v85
	v_max3_f32 v210, v82, v83, v210
	v_max3_f32 v213, v87, v88, v89
	v_max3_f32 v214, v91, v92, v93
	v_max3_f32 v210, v210, v86, v213
	v_max3_f32 v215, v95, v96, v97
	v_max3_f32 v210, v210, v90, v214
	v_max3_f32 v214, v210, v94, v215
	ds_bpermute_b32 v215, v153, v214
	v_max_f32_e32 v216, v68, v69
	v_max3_f32 v216, v66, v67, v216
	v_max3_f32 v217, v71, v72, v73
	v_max3_f32 v216, v216, v70, v217
	v_max3_f32 v217, v75, v76, v77
	v_max3_f32 v210, v216, v74, v217
	v_max3_f32 v213, v79, v80, v81
	v_max3_f32 v210, v210, v78, v213
	ds_bpermute_b32 v213, v153, v210
	s_waitcnt lgkmcnt(1)
	v_max_f32_e32 v214, v214, v215
	v_cmp_lt_f32_e32 vcc, s100, v214
	s_cbranch_vccz .LBB0_141
	v_max_f32_e32 v215, s101, v214
	v_max_f32_e32 v214, 0, v215
	v_exp_f32_e64 v214, -v214
	v_sub_f32_e32 v188, v188, v215
	v_sub_f32_e32 v189, v189, v215
	v_sub_f32_e32 v190, v190, v215
	v_sub_f32_e32 v191, v191, v215
	v_sub_f32_e32 v192, v192, v215
	v_sub_f32_e32 v193, v193, v215
	v_sub_f32_e32 v194, v194, v215
	v_sub_f32_e32 v195, v195, v215
	v_sub_f32_e32 v196, v196, v215
	v_sub_f32_e32 v197, v197, v215
	v_sub_f32_e32 v198, v198, v215
	v_sub_f32_e32 v199, v199, v215
	v_sub_f32_e32 v200, v200, v215
	v_sub_f32_e32 v201, v201, v215
	v_sub_f32_e32 v202, v202, v215
	v_sub_f32_e32 v203, v203, v215
	v_sub_f32_e32 v82, v82, v215
	v_sub_f32_e32 v83, v83, v215
	v_sub_f32_e32 v84, v84, v215
	v_sub_f32_e32 v85, v85, v215
	v_sub_f32_e32 v86, v86, v215
	v_sub_f32_e32 v87, v87, v215
	v_sub_f32_e32 v88, v88, v215
	v_sub_f32_e32 v89, v89, v215
	v_sub_f32_e32 v90, v90, v215
	v_sub_f32_e32 v91, v91, v215
	v_sub_f32_e32 v92, v92, v215
	v_sub_f32_e32 v93, v93, v215
	v_sub_f32_e32 v94, v94, v215
	v_sub_f32_e32 v95, v95, v215
	v_sub_f32_e32 v96, v96, v215
	v_sub_f32_e32 v97, v97, v215
	v_pk_mul_f32 v[64:65], v[64:65], v[214:215] op_sel_hi:[1,0]
	v_pk_mul_f32 v[62:63], v[62:63], v[214:215] op_sel_hi:[1,0]
	v_pk_mul_f32 v[60:61], v[60:61], v[214:215] op_sel_hi:[1,0]
	v_pk_mul_f32 v[58:59], v[58:59], v[214:215] op_sel_hi:[1,0]
	v_pk_mul_f32 v[56:57], v[56:57], v[214:215] op_sel_hi:[1,0]
	v_pk_mul_f32 v[54:55], v[54:55], v[214:215] op_sel_hi:[1,0]
	v_pk_mul_f32 v[52:53], v[52:53], v[214:215] op_sel_hi:[1,0]
	v_pk_mul_f32 v[50:51], v[50:51], v[214:215] op_sel_hi:[1,0]
	v_pk_mul_f32 v[48:49], v[48:49], v[214:215] op_sel_hi:[1,0]
	v_pk_mul_f32 v[46:47], v[46:47], v[214:215] op_sel_hi:[1,0]
	v_pk_mul_f32 v[44:45], v[44:45], v[214:215] op_sel_hi:[1,0]
	v_pk_mul_f32 v[42:43], v[42:43], v[214:215] op_sel_hi:[1,0]
	v_pk_mul_f32 v[40:41], v[40:41], v[214:215] op_sel_hi:[1,0]
	v_pk_mul_f32 v[38:39], v[38:39], v[214:215] op_sel_hi:[1,0]
	v_pk_mul_f32 v[36:37], v[36:37], v[214:215] op_sel_hi:[1,0]
	v_pk_mul_f32 v[34:35], v[34:35], v[214:215] op_sel_hi:[1,0]
	v_mul_f32_e32 v211, v211, v214

; #define LAS __attribute__((address_space(3)))
; #define MFMA32(a, b, c) __builtin_amdgcn_mfma_f32_32x32x16_bf16((a), (b), (c), 0, 0, 0)
; #define AT_LMAX(P, MX) do { MX = fmaxf(fmaxf(P[0], P[1]), fmaxf(P[2], P[3])); \
;         _Pragma("unroll") for (int i_ = 4; i_ < 16; i_ += 4) MX = fmaxf(fmaxf(MX, P[i_]), fmaxf(fmaxf(P[i_ + 1], P[i_ + 2]), P[i_ + 3])); } while (0)
; __device__ __forceinline__ void attn_unit(LAS unsigned char* lds, const GAS bf16_t* __restrict__ QR, const GAS float* __restrict__ ssq, const GAS float* __restrict__ RT, const GAS bf16_t* __restrict__ K, const GAS bf16_t* __restrict__ Vt, GAS bf16_t* __restrict__ A2, int b, int h, int qb, int tid, i ...
;     ...
;             for (int d0 = 0; d0 < 6; ++d0) { const bf16x8 a0 = *(const LAS bf16x8*)(kb + d0 * 32); pA = MFMA32(a0, qa[d0], pA); pB = MFMA32(a0, qc[d0], pB); }
;             u32x4 pwA0, pwA1, pwB0, pwB1;
;             float mxA, mxB; AT_LMAX(pA, mxA); AT_LMAX(pB, mxB);
;             { const float oa = __shfl_xor(mxA, 32), ob = __shfl_xor(mxB, 32); mxA = fmaxf(mxA, oa); mxB = fmaxf(mxB, ob); }
;             AT_SOFTMAX(pA, mxA, mA, lA, oA0, oA1, pwA0, pwA1);
;             AT_SOFTMAX(pB, mxB, mB, lB, oB0, oB1, pwB0, pwB1);
;             const LAS unsigned char* vb = sb + AT_VOFF + r32 * AT_VROW + hi * 16 + hh * 64;
; #pragma unroll
;             for (int ks = 0; ks < 2; ++ks) {
;                 const bf16x8 va0 = *(const LAS bf16x8*)(vb + ks * 32), va1 = *(const LAS bf16x8*)(vb + 32 * AT_VROW + ks * 32);
;                 const bf16x8 pa = __builtin_bit_cast(bf16x8, ks ? pwA1 : pwA0), pb = __builtin_bit_cast(bf16x8, ks ? pwB1 : pwB0);
;                 oA0 = MFMA32(va0, pa, oA0); oA1 = MFMA32(va1, pa, oA1); oB0 = MFMA32(va0, pb, oB0); oB1 = MFMA32(va1, pb, oB1);
;             }
.LBB0_143:
	s_mov_b32 s100, 0x41000000
	s_mov_b32 s101, 0
	v_exp_f32_e32 v210, v82
	v_exp_f32_e32 v213, v83
	v_exp_f32_e32 v214, v84
	v_exp_f32_e32 v215, v85
	v_exp_f32_e32 v216, v86
	v_exp_f32_e32 v217, v87
	v_exp_f32_e32 v218, v88
	v_exp_f32_e32 v219, v89
	v_cvt_pk_bf16_f32 v86, v210, v213
	v_exp_f32_e32 v90, v90
	v_add_f32_e32 v210, v213, v210
	v_exp_f32_e32 v91, v91
	v_add_f32_e32 v210, v214, v210
	v_exp_f32_e32 v92, v92
	v_add_f32_e32 v210, v215, v210
	v_exp_f32_e32 v93, v93
	v_add_f32_e32 v210, v216, v210
	v_exp_f32_e32 v213, v66
	v_exp_f32_e32 v94, v94
	v_cvt_pk_bf16_f32 v87, v214, v215
	v_add_f32_e32 v210, v217, v210
	v_exp_f32_e32 v214, v67
	v_exp_f32_e32 v95, v95
	v_add_f32_e32 v210, v218, v210
	v_exp_f32_e32 v215, v68
	v_exp_f32_e32 v96, v96
	v_cvt_pk_bf16_f32 v88, v216, v217
	v_add_f32_e32 v210, v219, v210
	v_exp_f32_e32 v216, v69
	v_exp_f32_e32 v97, v97
	v_cvt_pk_bf16_f32 v82, v90, v91
	v_add_f32_e32 v90, v90, v210
	v_exp_f32_e32 v217, v70
	v_cvt_pk_bf16_f32 v89, v218, v219
	v_add_f32_e32 v90, v91, v90
	v_exp_f32_e32 v218, v71
	v_add_f32_e32 v90, v92, v90
	v_exp_f32_e32 v219, v72
	v_add_f32_e32 v90, v93, v90
	v_exp_f32_e32 v220, v73
	v_add_f32_e32 v90, v94, v90
	v_exp_f32_e32 v221, v74
	v_add_f32_e32 v90, v95, v90
	v_exp_f32_e32 v222, v75
	v_add_f32_e32 v90, v96, v90
	v_exp_f32_e32 v223, v76
	v_add_f32_e32 v90, v97, v90
	v_exp_f32_e32 v224, v77
	v_add_f32_e32 v211, v211, v90
	v_exp_f32_e32 v225, v78
	v_exp_f32_e32 v226, v79
	v_add_u32_e32 v210, s24, v204
	v_cvt_pk_bf16_f32 v83, v92, v93
	v_exp_f32_e32 v227, v80
	v_exp_f32_e32 v228, v81
	ds_read_b128 v[74:77], v210 offset:17920
	ds_read_b128 v[78:81], v210 offset:13312
	ds_read_b128 v[90:93], v210 offset:13344
	v_cvt_pk_bf16_f32 v70, v213, v214
	v_cvt_pk_bf16_f32 v71, v215, v216
	v_cvt_pk_bf16_f32 v72, v217, v218
	v_cvt_pk_bf16_f32 v73, v219, v220
	s_waitcnt lgkmcnt(1)
	v_mfma_f32_32x32x16_bf16 v[50:65], v[78:81], v[86:89], v[50:65]
	v_cvt_pk_bf16_f32 v84, v94, v95
	v_cvt_pk_bf16_f32 v85, v96, v97
	v_cvt_pk_bf16_f32 v66, v221, v222
	v_cvt_pk_bf16_f32 v67, v223, v224
	v_cvt_pk_bf16_f32 v68, v225, v226
	v_cvt_pk_bf16_f32 v69, v227, v228
	v_mfma_f32_32x32x16_bf16 v[18:33], v[78:81], v[70:73], v[18:33]
	v_mfma_f32_32x32x16_bf16 v[2:17], v[74:77], v[70:73], v[2:17]
	v_add_f32_e32 v213, v214, v213
	v_add_f32_e32 v213, v215, v213
	v_add_f32_e32 v213, v216, v213
	v_add_f32_e32 v213, v217, v213
	v_add_f32_e32 v213, v218, v213
	v_add_f32_e32 v213, v219, v213
	v_add_f32_e32 v213, v220, v213
	v_add_f32_e32 v213, v221, v213
	v_add_f32_e32 v213, v222, v213
	v_add_f32_e32 v213, v223, v213
	v_add_f32_e32 v213, v224, v213
	v_add_f32_e32 v213, v225, v213
	v_add_f32_e32 v213, v226, v213
	v_add_f32_e32 v213, v227, v213
	v_add_f32_e32 v213, v228, v213
	v_add_f32_e32 v209, v209, v213
	ds_read_b128 v[70:73], v210 offset:17952
	v_mfma_f32_32x32x16_bf16 v[34:49], v[74:77], v[86:89], v[34:49]
	s_waitcnt lgkmcnt(1)
	v_mfma_f32_32x32x16_bf16 v[50:65], v[90:93], v[82:85], v[50:65]
	s_waitcnt lgkmcnt(0)
	v_mfma_f32_32x32x16_bf16 v[34:49], v[70:73], v[82:85], v[34:49]
	ds_read_b128 v[82:85], v212 offset:6656
	ds_read_b128 v[230:233], v212 offset:6688
	ds_read_b128 v[214:217], v212 offset:6720
	ds_read_b128 v[218:221], v212 offset:6752
	ds_read_b128 v[222:225], v212 offset:6784
	ds_read_b128 v[226:229], v212 offset:6816
	v_mfma_f32_32x32x16_bf16 v[18:33], v[90:93], v[66:69], v[18:33]
	v_mfma_f32_32x32x16_bf16 v[2:17], v[70:73], v[66:69], v[2:17]
	s_waitcnt lgkmcnt(5)
	v_mfma_f32_32x32x16_bf16 v[66:81], v[82:85], v[98:101], v[188:203]
	s_waitcnt lgkmcnt(4)
	v_mfma_f32_32x32x16_bf16 v[66:81], v[230:233], v[102:105], v[66:81]
	s_waitcnt lgkmcnt(3)
	v_mfma_f32_32x32x16_bf16 v[66:81], v[214:217], v[106:109], v[66:81]
	s_waitcnt lgkmcnt(2)
	v_mfma_f32_32x32x16_bf16 v[66:81], v[218:221], v[110:113], v[66:81]
	s_waitcnt lgkmcnt(1)
	v_mfma_f32_32x32x16_bf16 v[66:81], v[222:225], v[134:137], v[66:81]
	s_waitcnt lgkmcnt(0)
	v_mfma_f32_32x32x16_bf16 v[66:81], v[226:229], v[114:117], v[66:81]
	v_mfma_f32_32x32x16_bf16 v[82:97], v[82:85], v[118:121], v[234:249]
	v_mfma_f32_32x32x16_bf16 v[82:97], v[230:233], v[122:125], v[82:97]
	v_mfma_f32_32x32x16_bf16 v[82:97], v[214:217], v[126:129], v[82:97]
	v_mfma_f32_32x32x16_bf16 v[82:97], v[218:221], v[130:133], v[82:97]
	v_mfma_f32_32x32x16_bf16 v[82:97], v[222:225], v[138:141], v[82:97]
	v_mfma_f32_32x32x16_bf16 v[82:97], v[226:229], v[142:145], v[82:97]
	s_nop 5
	v_max_f32_e32 v250, v68, v69
	v_max3_f32 v179, v66, v67, v250
	v_max3_f32 v250, v71, v72, v73
	v_max3_f32 v251, v75, v76, v77
	v_max3_f32 v179, v179, v70, v250
	v_max3_f32 v252, v79, v80, v81
	v_max3_f32 v179, v179, v74, v251
	v_max3_f32 v230, v179, v78, v252
	ds_bpermute_b32 v231, v153, v230
	v_max_f32_e32 v212, v84, v85
	v_max3_f32 v212, v82, v83, v212
	v_max3_f32 v250, v87, v88, v89
	v_max3_f32 v212, v212, v86, v250
	v_max3_f32 v250, v91, v92, v93
	v_max3_f32 v212, v212, v90, v250
	v_max3_f32 v250, v95, v96, v97
	v_max3_f32 v212, v212, v94, v250
	ds_bpermute_b32 v179, v153, v212
	s_waitcnt lgkmcnt(1)
	v_max_f32_e32 v230, v230, v231
	v_cmp_lt_f32_e32 vcc, s100, v230
	s_cbranch_vccz .LBB0_145
	v_max_f32_e32 v231, s101, v230
	v_max_f32_e32 v230, 0, v231
	v_exp_f32_e64 v230, -v230
	v_sub_f32_e32 v188, v188, v231
	v_sub_f32_e32 v189, v189, v231
	v_sub_f32_e32 v190, v190, v231
	v_sub_f32_e32 v191, v191, v231
	v_sub_f32_e32 v192, v192, v231
	v_sub_f32_e32 v193, v193, v231
	v_sub_f32_e32 v194, v194, v231
	v_sub_f32_e32 v195, v195, v231
	v_sub_f32_e32 v196, v196, v231
	v_sub_f32_e32 v197, v197, v231
	v_sub_f32_e32 v198, v198, v231
	v_sub_f32_e32 v199, v199, v231
	v_sub_f32_e32 v200, v200, v231
	v_sub_f32_e32 v201, v201, v231
	v_sub_f32_e32 v202, v202, v231
	v_sub_f32_e32 v203, v203, v231
	v_sub_f32_e32 v66, v66, v231
	v_sub_f32_e32 v67, v67, v231
	v_sub_f32_e32 v68, v68, v231
	v_sub_f32_e32 v69, v69, v231
	v_sub_f32_e32 v70, v70, v231
	v_sub_f32_e32 v71, v71, v231
	v_sub_f32_e32 v72, v72, v231
	v_sub_f32_e32 v73, v73, v231
	v_sub_f32_e32 v74, v74, v231
	v_sub_f32_e32 v75, v75, v231
	v_sub_f32_e32 v76, v76, v231
	v_sub_f32_e32 v77, v77, v231
	v_sub_f32_e32 v78, v78, v231
	v_sub_f32_e32 v79, v79, v231
	v_sub_f32_e32 v80, v80, v231
	v_sub_f32_e32 v81, v81, v231
	v_pk_mul_f32 v[64:65], v[64:65], v[230:231] op_sel_hi:[1,0]
	v_pk_mul_f32 v[62:63], v[62:63], v[230:231] op_sel_hi:[1,0]
	v_pk_mul_f32 v[60:61], v[60:61], v[230:231] op_sel_hi:[1,0]
	v_pk_mul_f32 v[58:59], v[58:59], v[230:231] op_sel_hi:[1,0]
	v_pk_mul_f32 v[56:57], v[56:57], v[230:231] op_sel_hi:[1,0]
	v_pk_mul_f32 v[54:55], v[54:55], v[230:231] op_sel_hi:[1,0]
	v_pk_mul_f32 v[52:53], v[52:53], v[230:231] op_sel_hi:[1,0]
	v_pk_mul_f32 v[50:51], v[50:51], v[230:231] op_sel_hi:[1,0]
	v_pk_mul_f32 v[48:49], v[48:49], v[230:231] op_sel_hi:[1,0]
	v_pk_mul_f32 v[46:47], v[46:47], v[230:231] op_sel_hi:[1,0]
	v_pk_mul_f32 v[44:45], v[44:45], v[230:231] op_sel_hi:[1,0]
	v_pk_mul_f32 v[42:43], v[42:43], v[230:231] op_sel_hi:[1,0]
	v_pk_mul_f32 v[40:41], v[40:41], v[230:231] op_sel_hi:[1,0]
	v_pk_mul_f32 v[38:39], v[38:39], v[230:231] op_sel_hi:[1,0]
	v_pk_mul_f32 v[36:37], v[36:37], v[230:231] op_sel_hi:[1,0]
	v_pk_mul_f32 v[34:35], v[34:35], v[230:231] op_sel_hi:[1,0]
	v_mul_f32_e32 v211, v211, v230
